# sample-row norm phases moved to workgroups 192..255, grid barrier after them removed; GEMM K loop acquires a counter before sample-unit A loads (write-through XN)
# speedup vs baseline: 1.0254x; 1.0254x over previous
; #define LAS __attribute__((address_space(3)))
; __device__ __forceinline__ unsigned xb_add(unsigned* p, unsigned v) { return __hip_atomic_fetch_add(p, v, __ATOMIC_RELAXED, __HIP_MEMORY_SCOPE_AGENT); }
; __device__ __forceinline__ unsigned xb_xcc_id() { return (unsigned)__builtin_amdgcn_s_getreg((3 << 11) | 20) & 0xFu; }
; __global__ void __launch_bounds__(512, 2) hybrid_fwd(Params P) {
;     ...
;     LAS unsigned long long* ptab = (LAS unsigned long long*)(ldsl + PTAB_OFF);
;     if (threadIdx.x == 0) {
; #pragma unroll
;         for (int i = 0; i < 34; ++i) ptab[i] = (unsigned long long)P.in[i];
;         ptab[34] = (unsigned long long)P.out; ptab[35] = (unsigned long long)P.ws;
;         ((volatile LAS unsigned*)(ldsl + XBST_OFF))[0] = 0u; ((volatile LAS unsigned*)(ldsl + XBST_OFF))[1] = 0u;
;         (void)xb_add((unsigned*)P.ws + XB_XCNT(xb_xcc_id()), 1u); }
_Z10hybrid_fwd6Params:
	v_mov_b32_e32 v255, 0
	s_add_u32 s4, s0, 0x128
	v_writelane_b32 v253, s2, 0
	s_load_dword s2, s[0:1], 0x128
	v_and_b32_e32 v1, 0x3ff, v0
	v_and_b32_e32 v0, 0x3fffffff, v0
	s_addc_u32 s5, s1, 0
	v_readfirstlane_b32 s26, v1
	s_waitcnt lgkmcnt(0)
	v_writelane_b32 v253, s2, 1
	v_cmp_eq_u32_e32 vcc, 0, v1
	s_and_saveexec_b64 s[2:3], vcc
	s_cbranch_execz .LBB0_13
	s_load_dwordx16 s[8:23], s[0:1], 0x0
	s_add_i32 s4, 0, 0x20400
	v_mov_b32_e32 v4, s4
	s_add_i32 s4, 0, 0x20410
	s_load_dwordx16 s[36:51], s[0:1], 0x80
	s_waitcnt lgkmcnt(0)
	v_mov_b32_e32 v0, s8
	v_mov_b32_e32 v1, s9
	v_mov_b32_e32 v2, s10
	v_mov_b32_e32 v3, s11
	ds_write_b128 v4, v[0:3]
	v_mov_b32_e32 v0, s12
	v_mov_b32_e32 v1, s13
	v_mov_b32_e32 v2, s14
	v_mov_b32_e32 v3, s15
	v_mov_b32_e32 v4, s4
	s_add_i32 s4, 0, 0x20420
	ds_write_b128 v4, v[0:3]
	v_mov_b32_e32 v0, s16
	v_mov_b32_e32 v1, s17
	v_mov_b32_e32 v2, s18
	v_mov_b32_e32 v3, s19
	v_mov_b32_e32 v4, s4
	s_load_dwordx16 s[4:19], s[0:1], 0x40
	ds_write_b128 v4, v[0:3]
	v_mov_b32_e32 v0, s20
	s_add_i32 s20, 0, 0x20430
	v_mov_b32_e32 v1, s21
	v_mov_b32_e32 v2, s22
	v_mov_b32_e32 v3, s23
	v_mov_b32_e32 v4, s20
	ds_write_b128 v4, v[0:3]
	s_waitcnt lgkmcnt(0)
	v_mov_b32_e32 v0, s4
	s_add_i32 s4, 0, 0x20440
	v_mov_b32_e32 v1, s5
	v_mov_b32_e32 v2, s6
	v_mov_b32_e32 v3, s7
	v_mov_b32_e32 v4, s4
	s_add_i32 s4, 0, 0x20450
	ds_write_b128 v4, v[0:3]
	v_mov_b32_e32 v0, s8
	v_mov_b32_e32 v1, s9
	v_mov_b32_e32 v2, s10
	v_mov_b32_e32 v3, s11
	v_mov_b32_e32 v4, s4
	s_add_i32 s4, 0, 0x20460
	ds_write_b128 v4, v[0:3]
	v_mov_b32_e32 v0, s12
	v_mov_b32_e32 v1, s13
	v_mov_b32_e32 v2, s14
	v_mov_b32_e32 v3, s15
	v_mov_b32_e32 v4, s4
	s_add_i32 s4, 0, 0x20470
	ds_write_b128 v4, v[0:3]
	v_mov_b32_e32 v0, s16
	v_mov_b32_e32 v1, s17
	v_mov_b32_e32 v2, s18
	v_mov_b32_e32 v3, s19
	v_mov_b32_e32 v4, s4
	s_add_i32 s4, 0, 0x20480
	ds_write_b128 v4, v[0:3]
	v_mov_b32_e32 v0, s36
	v_mov_b32_e32 v1, s37
	v_mov_b32_e32 v2, s38
	v_mov_b32_e32 v3, s39
	v_mov_b32_e32 v4, s4
	s_add_i32 s4, 0, 0x20490
	ds_write_b128 v4, v[0:3]
	v_mov_b32_e32 v0, s40
	v_mov_b32_e32 v1, s41
	v_mov_b32_e32 v2, s42
	v_mov_b32_e32 v3, s43
	v_mov_b32_e32 v4, s4
	s_add_i32 s4, 0, 0x204a0
	ds_write_b128 v4, v[0:3]
	v_mov_b32_e32 v4, s4
	s_load_dwordx16 s[4:19], s[0:1], 0xc0
	v_mov_b32_e32 v0, s44
	v_mov_b32_e32 v1, s45
	v_mov_b32_e32 v2, s46
	v_mov_b32_e32 v3, s47
	s_add_i32 s20, 0, 0x204b0
	ds_write_b128 v4, v[0:3]
	v_mov_b32_e32 v0, s48
	v_mov_b32_e32 v1, s49
	v_mov_b32_e32 v2, s50
	v_mov_b32_e32 v3, s51
	v_mov_b32_e32 v4, s20
	ds_write_b128 v4, v[0:3]
	s_waitcnt lgkmcnt(0)
	v_mov_b32_e32 v0, s4
	s_add_i32 s4, 0, 0x204c0
	v_mov_b32_e32 v1, s5
	v_mov_b32_e32 v2, s6
	v_mov_b32_e32 v3, s7
	v_mov_b32_e32 v4, s4
	s_add_i32 s4, 0, 0x204d0
	ds_write_b128 v4, v[0:3]
	v_mov_b32_e32 v0, s8
	v_mov_b32_e32 v1, s9
	v_mov_b32_e32 v2, s10
	v_mov_b32_e32 v3, s11
	v_mov_b32_e32 v4, s4
	s_add_i32 s4, 0, 0x204e0
	ds_write_b128 v4, v[0:3]
	v_mov_b32_e32 v4, s4
	s_load_dwordx8 s[4:11], s[0:1], 0x100
	v_mov_b32_e32 v0, s12
	v_mov_b32_e32 v1, s13
	v_mov_b32_e32 v2, s14
	v_mov_b32_e32 v3, s15
	s_add_i32 s12, 0, 0x204f0
	ds_write_b128 v4, v[0:3]
	v_mov_b32_e32 v0, s16
	v_mov_b32_e32 v1, s17
	v_mov_b32_e32 v2, s18
	v_mov_b32_e32 v3, s19
	v_mov_b32_e32 v4, s12
	ds_write_b128 v4, v[0:3]
	s_waitcnt lgkmcnt(0)
	v_mov_b32_e32 v0, s4
	s_add_i32 s4, 0, 0x20500
	v_mov_b32_e32 v1, s5
	v_mov_b32_e32 v2, s6
	v_mov_b32_e32 v3, s7
	v_mov_b32_e32 v4, s4
	s_add_i32 s4, 0, 0x20510
	ds_write_b128 v4, v[0:3]
	v_mov_b32_e32 v0, s8
	v_mov_b32_e32 v1, s9
	v_mov_b32_e32 v2, s10
	v_mov_b32_e32 v3, s11
	v_mov_b32_e32 v4, s4
	s_add_i32 s4, 0, 0x20600
	ds_write_b128 v4, v[0:3]
	v_mov_b32_e32 v0, 0
	v_mov_b32_e32 v1, s4
	s_add_i32 s4, 0, 0x20604
	s_mov_b64 s[24:25], exec
	ds_write_b32 v1, v0
	v_mov_b32_e32 v1, s4
	ds_write_b32 v1, v0
	v_mbcnt_lo_u32_b32 v0, s24, 0
	v_mbcnt_hi_u32_b32 v0, s25, v0
	s_getreg_b32 s4, hwreg(HW_REG_XCC_ID, 0, 4)
	v_cmp_eq_u32_e32 vcc, 0, v0
	s_and_b64 exec, exec, vcc
	s_cbranch_execz .LBB0_13
	s_lshl_b32 s4, s4, 8
	s_and_b32 s4, s4, 0xf00
	s_bcnt1_i32_b64 s5, s[24:25]
	v_mov_b32_e32 v0, s4
	v_mov_b32_e32 v1, s5
	global_atomic_add v0, v1, s[10:11] offset:1024

; #define PG8_STAGE(bufoff, gbase, voff) do { _Pragma("unroll") for (int _i = 0; _i < 2; ++_i) \
;         __builtin_amdgcn_global_load_lds((const unsigned*)((const char*)(gbase) + (voff)[_i]), (LAS unsigned*)(lds + (bufoff) + ldsw + _i * 8192), 16, 0, 0); } while (0)
; #define PG8_LDA(dst, b, h) do { _Pragma("unroll") for (int m = 0; m < 4; ++m) _Pragma("unroll") for (int k = 0; k < 2; ++k) dst[m][k] = *(const LAS bf16x8*)(lds + PG8_SA(b, h) + aoff + m * 2048 + k * 1024); } while (0)
; #define PG8_LDB(dst, b, h) do { _Pragma("unroll") for (int n = 0; n < 2; ++n) _Pragma("unroll") for (int k = 0; k < 2; ++k) dst[n][k] = *(const LAS bf16x8*)(lds + PG8_SB(b, h) + boff + n * 2048 + k * 1024); } while (0)
; #define PG8_SCHED __builtin_amdgcn_sched_barrier(0)
; template <class Epi, bool ALIGN_EPI>
; __device__ __forceinline__ void gemm_phase(LAS unsigned char* lds, const Gemm g, const Order& S, const Epi& E, const int wave_id) {
;     ...
;         const bool has_next = S.next(ui + 1, nxt);
;         const char* nA = has_next ? (const char*)g.A + (size_t)nxt.z * g.sAz + (size_t)nxt.pm * 2 * hstepA + (size_t)nxt.k0 * 2 : cA;
;         const char* nB = has_next ? (const char*)g.Bt + (size_t)nxt.z * g.sBz + (size_t)nxt.pn * 2 * hstepB + (size_t)nxt.k0 * 2 : cB;
;         const int nt = cur.nt;
;         for (int t = 0; t < nt; t += 2) {
;             const bool last = (t == nt - 2);
;             const char* a1 = cA + (size_t)(t + 1) * kstep;
;             const char* a2 = last ? nA : cA + (size_t)(t + 2) * kstep; const char* b2 = last ? nB : cB + (size_t)(t + 2) * kstep;
;             const char* a3 = a2 + kstep; const char* b3 = b2 + kstep;
;             PG8_LDB(B0, 0, 0); PG8_LDB(B1, 0, 1); PG8_SCHED; PG8_LDA(At, 0, 0); PG8_STAGE(PG8_SA(1, 1), a1 + hstepA, voffA);
.Lmy_ip_issue:
	s_cmp_lt_i32 s36, 64
	s_cbranch_scc1 .Lmy_ip_cont
	s_cmp_eq_u64 s[0:1], 0
	s_cbranch_scc1 .Lmy_ip_cont
	s_add_u32 s98, s53, 0xf4000148
	s_addc_u32 s99, s54, -1
	v_mov_b32_e32 v255, 0
	global_load_dword v255, v255, s[98:99] sc0 sc1
	s_branch .Lmy_ip_cont
.Lmy_ip_check:
	s_cmp_lt_i32 s36, 64
	s_cbranch_scc1 .Lmy_ip_cont
	s_cmp_eq_u64 s[0:1], 0
	s_cbranch_scc1 .Lmy_ip_cont
	s_lshl_b32 s74, s96, 10
	v_readfirstlane_b32 s98, v255
	s_cmp_ge_u32 s98, s74
	s_cbranch_scc1 .Lmy_ip_cont
	s_mov_b32 s32, 0
.Lmy_ip_slow:
	s_waitcnt vmcnt(0)
	v_readfirstlane_b32 s98, v255
	s_cmp_ge_u32 s98, s74
	s_cbranch_scc1 .Lmy_ip_cont
	s_add_i32 s32, s32, 1
	s_cmp_lt_u32 s32, 0x800
	s_cbranch_scc0 .Lmy_ip_cont
	s_sleep 1
	s_add_u32 s98, s53, 0xf4000148
	s_addc_u32 s99, s54, -1
	v_mov_b32_e32 v255, 0
	global_load_dword v255, v255, s[98:99] sc0 sc1
	s_branch .Lmy_ip_slow

; #define PG8_STAGE(bufoff, gbase, voff) do { _Pragma("unroll") for (int _i = 0; _i < 2; ++_i) \
;         __builtin_amdgcn_global_load_lds((const unsigned*)((const char*)(gbase) + (voff)[_i]), (LAS unsigned*)(lds + (bufoff) + ldsw + _i * 8192), 16, 0, 0); } while (0)
; #define PG8_LDA(dst, b, h) do { _Pragma("unroll") for (int m = 0; m < 4; ++m) _Pragma("unroll") for (int k = 0; k < 2; ++k) dst[m][k] = *(const LAS bf16x8*)(lds + PG8_SA(b, h) + aoff + m * 2048 + k * 1024); } while (0)
; #define PG8_LDB(dst, b, h) do { _Pragma("unroll") for (int n = 0; n < 2; ++n) _Pragma("unroll") for (int k = 0; k < 2; ++k) dst[n][k] = *(const LAS bf16x8*)(lds + PG8_SB(b, h) + boff + n * 2048 + k * 1024); } while (0)
; #define PG8_SCHED __builtin_amdgcn_sched_barrier(0)
; template <class Epi, bool ALIGN_EPI>
; __device__ __forceinline__ void gemm_phase(LAS unsigned char* lds, const Gemm g, const Order& S, const Epi& E, const int wave_id) {
;     ...
;         for (int t = 0; t < nt; t += 2) {
;             const bool last = (t == nt - 2);
;             const char* a1 = cA + (size_t)(t + 1) * kstep;
;             const char* a2 = last ? nA : cA + (size_t)(t + 2) * kstep; const char* b2 = last ? nB : cB + (size_t)(t + 2) * kstep;
;             const char* a3 = a2 + kstep; const char* b3 = b2 + kstep;
;             PG8_LDB(B0, 0, 0); PG8_LDB(B1, 0, 1); PG8_SCHED; PG8_LDA(At, 0, 0); PG8_STAGE(PG8_SA(1, 1), a1 + hstepA, voffA);
.LBB0_410:
	s_cmp_eq_u32 s48, 8
	s_cbranch_scc1 .Lmy_ip_issue
	s_cmp_eq_u32 s48, 12
	s_cbranch_scc1 .Lmy_ip_check

; #define INP(i) ((const float*)ld_ptr(pb, (i)))
; template <bool FINAL>
; __device__ __forceinline__ void norm_rows(const float* xp, const float* xs, const float* X, const float* g, const float* sh, const float* sc, bf16_t* XN, float* out, int gw, int NGW, int lane, const float* part, int nsplit) {
;     f32x4 vnext[4];
;     if (gw < M) { const float* xr0 = xp ? (gw < MP ? xp + (size_t)gw * D : xs + (size_t)(gw - MP) * D) : X + (size_t)gw * D;
; #pragma unroll
;         for (int j = 0; j < 4; ++j) vnext[j] = *(const f32x4*)(xr0 + 4 * lane + 256 * j); }
;     for (int row = gw; row < M; row += NGW) {
; __global__ void __launch_bounds__(512, 2) hybrid_fwd(Params P) {
;     ...
;         norm_rows<false>(nullptr, nullptr, X, INP(10) + l * D, (MOD + (size_t)l * NMODROWS * 6144) + 3072, (MOD + (size_t)l * NMODROWS * 6144) + 4096, XN, nullptr, gw, NGW, lane, (const float*)(ws + WS_PART), D / 256);
.LBB0_1707:
	s_andn2_b64 vcc, exec, s[0:1]
	s_cbranch_vccnz .LBB0_1769
	v_readlane_b32 s1, v253, 7
	v_readlane_b32 s0, v253, 0
	v_readlane_b32 s18, v253, 1
	v_readlane_b32 s12, v253, 2
	v_mov_b32_e32 v0, s1
	v_mbcnt_lo_u32_b32 v44, -1, 0
	v_mbcnt_hi_u32_b32 v44, -1, v44
	ds_read2_b64 v[0:3], v0 offset0:10 offset1:35
	s_lshl_b32 s0, s0, 3
	s_add_i32 s0, s0, s12
	s_add_i32 s0, s0, 0x3a00
	s_cmpk_lt_i32 s0, 0x4000
	s_cselect_b32 s0, 0x7fff, s0
	s_cmpk_gt_i32 s0, 0x41ff
	s_mov_b32 s13, 0x200000
	s_waitcnt lgkmcnt(0)
	v_readfirstlane_b32 s3, v3
	v_readfirstlane_b32 s2, v2
	v_readfirstlane_b32 s1, v1
	v_readfirstlane_b32 s5, v0
	s_mov_b32 s16, 0x600000
	s_cbranch_scc1 .LBB0_1715
	s_mul_i32 s74, s96, 0xc6000
	s_lshl_b32 s4, s18, 3
	s_lshl_b64 s[6:7], s[74:75], 2
	s_add_u32 s6, s2, s6
	s_addc_u32 s7, s3, s7
	s_add_u32 s8, s2, 0x7e00000
	s_addc_u32 s9, s3, 0
	s_lshl_b32 s74, s96, 10
	s_lshl_b64 s[10:11], s[74:75], 2
	s_add_u32 s10, s5, s10
	s_addc_u32 s11, s1, s11
	s_ashr_i32 s1, s0, 31
	s_lshl_b64 s[14:15], s[0:1], 12
	v_lshlrev_b32_e32 v12, 2, v44
	s_add_u32 s14, s8, s14
	v_ashrrev_i32_e32 v13, 31, v12
	s_addc_u32 s15, s9, s15
	v_lshlrev_b64 v[14:15], 2, v[12:13]
	v_lshl_add_u64 v[0:1], s[14:15], 0, v[14:15]
	global_load_dwordx4 v[28:31], v[0:1], off
	global_load_dwordx4 v[8:11], v[0:1], off offset:1024
	global_load_dwordx4 v[4:7], v[0:1], off offset:2048
	s_nop 0
	global_load_dwordx4 v[0:3], v[0:1], off offset:3072
	v_lshl_add_u64 v[16:17], s[2:3], 0, v[14:15]
	v_lshl_add_u64 v[34:35], s[8:9], 0, v[14:15]
	v_lshl_add_u64 v[36:37], s[10:11], 0, v[14:15]
	v_lshl_add_u64 v[14:15], s[6:7], 0, v[14:15]
	s_mov_b64 s[6:7], 0x804000
	v_lshl_add_u64 v[38:39], v[14:15], 0, s[6:7]
	s_mov_b64 s[6:7], 0x803000
	v_lshl_add_u64 v[40:41], v[14:15], 0, s[6:7]
	s_lshl_b64 s[6:7], s[0:1], 11
	s_add_u32 s6, s2, s6
	s_addc_u32 s7, s3, s7
	s_mov_b64 s[14:15], 0x13c00000
	v_lshl_add_u64 v[12:13], v[12:13], 1, s[6:7]
	s_mov_b64 s[6:7], 0xc000000
	s_ashr_i32 s5, s4, 31
	v_lshl_add_u64 v[32:33], v[16:17], 0, s[14:15]
	v_lshl_add_u64 v[42:43], v[12:13], 0, s[6:7]
	s_lshl_b64 s[6:7], s[4:5], 11
	s_branch .LBB0_1711
; __device__ __forceinline__ unsigned cvt_pk_bf16(float lo, float hi) { const f32x2_t v = {lo, hi}; const bf16x2_t b = __builtin_convertvector(v, bf16x2_t); return __builtin_bit_cast(unsigned, b); }
; template <bool FINAL>
; __device__ __forceinline__ void norm_rows(const float* xp, const float* xs, const float* X, const float* g, const float* sh, const float* sc, bf16_t* XN, float* out, int gw, int NGW, int lane, const float* part, int nsplit) {
;     ...
;         for (int j = 0; j < 4; ++j) s += (v[j][0] * v[j][0] + v[j][1] * v[j][1]) + (v[j][2] * v[j][2] + v[j][3] * v[j][3]);
;         const float rstd = 1.0f / sqrtf(wave_sum(s) * (1.0f / D) + EPS);
;         const int mr = mod_row(row);
;         if (!FINAL && xp && row >= MP) {
; #pragma unroll
;             for (int j = 0; j < 4; ++j) *(f32x4*)((float*)X + (size_t)row * D + 4 * lane + 256 * j) = v[j]; }
; #pragma unroll
;         for (int j = 0; j < 4; ++j) { const int col = 4 * lane + 256 * j; const f32x4 gg = *(const f32x4*)(g + col);
;             if (FINAL) { *(f32x4*)(out + (size_t)row * D + col) = v[j] * rstd * gg; }
;             else { const f32x4 s1 = *(const f32x4*)(sc + (size_t)mr * 6144 + col), s0 = *(const f32x4*)(sh + (size_t)mr * 6144 + col);
;                 const f32x4 h = v[j] * rstd * gg * (s1 + 1.0f) + s0;
;                 *(u32x2*)(XN + (size_t)row * D + col) = (u32x2){cvt_pk_bf16(h[0], h[1]), cvt_pk_bf16(h[2], h[3])}; } }
.LBB0_1710:
	v_mul_f32_e32 v45, v29, v29
	v_mul_f32_e32 v46, v31, v31
	v_fmac_f32_e32 v45, v28, v28
	v_fmac_f32_e32 v46, v30, v30
	v_add_f32_e32 v45, v45, v46
	v_mul_f32_e32 v46, v9, v9
	v_mul_f32_e32 v47, v11, v11
	v_fmac_f32_e32 v46, v8, v8
	v_fmac_f32_e32 v47, v10, v10
	v_add_f32_e32 v46, v46, v47
	v_add_f32_e32 v45, v45, v46
	v_mul_f32_e32 v46, v5, v5
	v_mul_f32_e32 v47, v7, v7
	v_fmac_f32_e32 v46, v4, v4
	v_fmac_f32_e32 v47, v6, v6
	v_add_f32_e32 v46, v46, v47
	v_add_f32_e32 v45, v46, v45
	v_mul_f32_e32 v46, v1, v1
	v_mul_f32_e32 v47, v3, v3
	v_fmac_f32_e32 v46, v0, v0
	v_fmac_f32_e32 v47, v2, v2
	v_add_f32_e32 v46, v46, v47
	v_add_f32_e32 v45, v46, v45
	ds_swizzle_b32 v46, v45 offset:swizzle(SWAP,1)
	s_waitcnt lgkmcnt(0)
	v_add_f32_e32 v45, v45, v46
	ds_swizzle_b32 v46, v45 offset:swizzle(SWAP,2)
	s_waitcnt lgkmcnt(0)
	v_add_f32_e32 v45, v45, v46
	ds_swizzle_b32 v46, v45 offset:swizzle(SWAP,4)
	s_waitcnt lgkmcnt(0)
	v_add_f32_e32 v45, v45, v46
	ds_swizzle_b32 v46, v45 offset:swizzle(SWAP,8)
	s_waitcnt lgkmcnt(0)
	v_add_f32_e32 v45, v45, v46
	ds_swizzle_b32 v46, v45 offset:swizzle(SWAP,16)
	s_waitcnt lgkmcnt(0)
	v_add_f32_e32 v45, v45, v46
	v_mov_b32_e32 v62, v45
	s_nop 1
	v_permlane32_swap_b32 v45, v62
	s_nop 1
	v_add_f32_e32 v45, v45, v62
	v_fmamk_f32 v45, v45, 0x3a800000, v202
	v_mul_f32_e32 v62, 0x4f800000, v45
	v_cmp_gt_f32_e32 vcc, s95, v45
	s_nop 1
	v_cndmask_b32_e32 v45, v45, v62, vcc
	v_sqrt_f32_e32 v62, v45
	s_nop 0
	v_add_u32_e32 v63, -1, v62
	v_add_u32_e32 v64, 1, v62
	v_fma_f32 v65, -v63, v62, v45
	v_fma_f32 v66, -v64, v62, v45
	v_cmp_ge_f32_e64 s[0:1], 0, v65
	s_nop 1
	v_cndmask_b32_e64 v62, v62, v63, s[0:1]
	v_cmp_lt_f32_e64 s[0:1], 0, v66
	s_nop 1
	v_cndmask_b32_e64 v62, v62, v64, s[0:1]
	v_mul_f32_e32 v63, 0x37800000, v62
	v_cndmask_b32_e32 v62, v62, v63, vcc
	v_cmp_class_f32_e32 vcc, v45, v203
	s_nop 1
	v_cndmask_b32_e32 v45, v62, v45, vcc
	v_div_scale_f32 v62, s[0:1], v45, v45, 1.0
	v_rcp_f32_e32 v63, v62
	v_div_scale_f32 v64, vcc, 1.0, v45, 1.0
	s_mov_b32 s0, s8
	v_fma_f32 v65, -v62, v63, 1.0
	v_fmac_f32_e32 v63, v65, v63
	v_mul_f32_e32 v65, v64, v63
	v_fma_f32 v66, -v62, v65, v64
	v_fmac_f32_e32 v65, v66, v63
	v_fma_f32 v62, -v62, v65, v64
	v_div_fmas_f32 v62, v62, v63, v65
	v_div_fixup_f32 v62, v62, v45, 1.0
	v_pk_mul_f32 v[30:31], v[30:31], v[62:63] op_sel_hi:[1,0]
	v_pk_mul_f32 v[28:29], v[28:29], v[62:63] op_sel_hi:[1,0]
	v_pk_mul_f32 v[10:11], v[10:11], v[62:63] op_sel_hi:[1,0]
	v_pk_mul_f32 v[8:9], v[8:9], v[62:63] op_sel_hi:[1,0]
	v_pk_mul_f32 v[6:7], v[6:7], v[62:63] op_sel_hi:[1,0]
	v_pk_mul_f32 v[4:5], v[4:5], v[62:63] op_sel_hi:[1,0]
	v_pk_mul_f32 v[2:3], v[2:3], v[62:63] op_sel_hi:[1,0]
	v_pk_mul_f32 v[0:1], v[0:1], v[62:63] op_sel_hi:[1,0]
	s_andn2_b64 vcc, exec, s[10:11]
	s_waitcnt vmcnt(4)
	v_pk_mul_f32 v[28:29], v[112:113], v[28:29]
	v_pk_mul_f32 v[30:31], v[114:115], v[30:31]
	v_pk_add_f32 v[130:131], v[130:131], 1.0 op_sel_hi:[1,0]
	v_pk_add_f32 v[128:129], v[128:129], 1.0 op_sel_hi:[1,0]
	v_pk_fma_f32 v[30:31], v[130:131], v[30:31], v[146:147]
	v_pk_fma_f32 v[28:29], v[128:129], v[28:29], v[144:145]
	s_nop 0
	v_cvt_pk_bf16_f32 v28, v28, v29
	v_cvt_pk_bf16_f32 v29, v30, v31
	global_store_dwordx2 v[42:43], v[28:29], off sc0 sc1
	v_pk_mul_f32 v[8:9], v[116:117], v[8:9]
	v_pk_mul_f32 v[10:11], v[118:119], v[10:11]
	v_pk_add_f32 v[134:135], v[134:135], 1.0 op_sel_hi:[1,0]
	v_pk_add_f32 v[132:133], v[132:133], 1.0 op_sel_hi:[1,0]
	v_pk_fma_f32 v[10:11], v[134:135], v[10:11], v[150:151]
	v_pk_fma_f32 v[8:9], v[132:133], v[8:9], v[148:149]
	s_nop 0
	v_cvt_pk_bf16_f32 v8, v8, v9
	v_cvt_pk_bf16_f32 v9, v10, v11
	global_store_dwordx2 v[42:43], v[8:9], off offset:512 sc0 sc1
	v_pk_mul_f32 v[4:5], v[120:121], v[4:5]
	v_pk_mul_f32 v[6:7], v[122:123], v[6:7]
	v_pk_add_f32 v[138:139], v[138:139], 1.0 op_sel_hi:[1,0]
	v_pk_add_f32 v[136:137], v[136:137], 1.0 op_sel_hi:[1,0]
	v_pk_fma_f32 v[6:7], v[138:139], v[6:7], v[154:155]
	v_pk_fma_f32 v[4:5], v[136:137], v[4:5], v[152:153]
	s_nop 0
	v_cvt_pk_bf16_f32 v4, v4, v5
	v_cvt_pk_bf16_f32 v5, v6, v7
	global_store_dwordx2 v[42:43], v[4:5], off offset:1024 sc0 sc1
	v_pk_mul_f32 v[0:1], v[124:125], v[0:1]
	v_pk_mul_f32 v[2:3], v[126:127], v[2:3]
	v_pk_add_f32 v[142:143], v[142:143], 1.0 op_sel_hi:[1,0]
	v_pk_add_f32 v[140:141], v[140:141], 1.0 op_sel_hi:[1,0]
	v_pk_fma_f32 v[2:3], v[142:143], v[2:3], v[158:159]
	v_pk_fma_f32 v[0:1], v[140:141], v[0:1], v[156:157]
	s_nop 0
	v_cvt_pk_bf16_f32 v0, v0, v1
	v_cvt_pk_bf16_f32 v1, v2, v3
	global_store_dwordx2 v[42:43], v[0:1], off offset:1536 sc0 sc1
	s_waitcnt vmcnt(4)
	v_mov_b32_e32 v28, v16
	v_mov_b32_e32 v29, v17
	v_mov_b32_e32 v30, v18
	v_mov_b32_e32 v31, v19
	v_mov_b32_e32 v8, v20
	v_mov_b32_e32 v9, v21
	v_mov_b32_e32 v10, v22
	v_mov_b32_e32 v11, v23
	v_mov_b32_e32 v4, v24
	v_mov_b32_e32 v5, v25
	v_mov_b32_e32 v6, v26
	v_mov_b32_e32 v7, v27
	v_mov_b32_e32 v0, v12
	v_mov_b32_e32 v1, v13
	v_mov_b32_e32 v2, v14
	v_mov_b32_e32 v3, v15
	v_lshl_add_u64 v[42:43], v[42:43], 0, s[6:7]
	s_cbranch_vccz .Lmy_nf2_arr

; #define INP(i) ((const float*)ld_ptr(pb, (i)))
; #define PHASE_END if (ph + 1 < hi) grid_barrier((unsigned*)ws, (unsigned)G, tid, (volatile LAS unsigned*)(ldsl + XBST_OFF)); } ++ph;
; __global__ void __launch_bounds__(512, 2) hybrid_fwd(Params P) {
;     ...
;         PHASE_BEGIN
;         norm_rows<false>(nullptr, nullptr, X, INP(10) + l * D, (MOD + (size_t)l * NMODROWS * 6144) + 3072, (MOD + (size_t)l * NMODROWS * 6144) + 4096, XN, nullptr, gw, NGW, lane, (const float*)(ws + WS_PART), D / 256);
;         PHASE_END
.Lmy_nf2_arr:
	s_waitcnt vmcnt(0)
	s_mov_b64 exec, 1
	v_mov_b32_e32 v0, 0x148
	v_mov_b32_e32 v1, 1
	global_atomic_add v0, v1, s[2:3]
	s_mov_b64 exec, -1
.LBB0_1715:
	s_add_i32 s22, s73, 6
	s_branch .LBB0_1769
	s_waitcnt vmcnt(0) lgkmcnt(0)
	s_lshl_b32 s0, s12, 6
	v_sub_u32_e32 v0, 0, v44
	v_cmp_eq_u32_e32 vcc, s0, v0
	s_waitcnt vmcnt(0)
	s_barrier
	s_and_saveexec_b64 s[0:1], vcc
	s_cbranch_execz .LBB0_1768
	v_readlane_b32 s5, v253, 8
	s_getreg_b32 s4, hwreg(HW_REG_XCC_ID, 0, 4)
	s_and_b32 s19, s4, 15
	v_mov_b32_e32 v0, s5
	ds_read_b32 v2, v0
	v_readlane_b32 s5, v253, 9
	s_waitcnt lgkmcnt(0)
	v_cmp_ne_u32_e32 vcc, 0, v2
	v_mov_b32_e32 v0, s5
	ds_read_b32 v0, v0
	s_cbranch_vccnz .LBB0_1732
	s_add_u32 s4, s2, 0x1000
	s_addc_u32 s5, s3, 0
	s_add_u32 s6, s2, 0x1100
	s_addc_u32 s7, s3, 0
	s_add_u32 s8, s2, 0x1200
	s_addc_u32 s9, s3, 0
	s_add_u32 s10, s2, 0x1300
	s_addc_u32 s11, s3, 0
	s_mov_b32 s20, 1
	s_branch .LBB0_1720

; #define PG8_STAGE(bufoff, gbase, voff) do { _Pragma("unroll") for (int _i = 0; _i < 2; ++_i) \
;         __builtin_amdgcn_global_load_lds((const unsigned*)((const char*)(gbase) + (voff)[_i]), (LAS unsigned*)(lds + (bufoff) + ldsw + _i * 8192), 16, 0, 0); } while (0)
; #define PG8_LDA(dst, b, h) do { _Pragma("unroll") for (int m = 0; m < 4; ++m) _Pragma("unroll") for (int k = 0; k < 2; ++k) dst[m][k] = *(const LAS bf16x8*)(lds + PG8_SA(b, h) + aoff + m * 2048 + k * 1024); } while (0)
; #define PG8_LDB(dst, b, h) do { _Pragma("unroll") for (int n = 0; n < 2; ++n) _Pragma("unroll") for (int k = 0; k < 2; ++k) dst[n][k] = *(const LAS bf16x8*)(lds + PG8_SB(b, h) + boff + n * 2048 + k * 1024); } while (0)
; #define PG8_SCHED __builtin_amdgcn_sched_barrier(0)
; template <class Epi, bool ALIGN_EPI>
; __device__ __forceinline__ void gemm_phase(LAS unsigned char* lds, const Gemm g, const Order& S, const Epi& E, const int wave_id) {
;     ...
;         const bool has_next = S.next(ui + 1, nxt);
;         const char* nA = has_next ? (const char*)g.A + (size_t)nxt.z * g.sAz + (size_t)nxt.pm * 2 * hstepA + (size_t)nxt.k0 * 2 : cA;
;         const char* nB = has_next ? (const char*)g.Bt + (size_t)nxt.z * g.sBz + (size_t)nxt.pn * 2 * hstepB + (size_t)nxt.k0 * 2 : cB;
;         const int nt = cur.nt;
;         for (int t = 0; t < nt; t += 2) {
;             const bool last = (t == nt - 2);
;             const char* a1 = cA + (size_t)(t + 1) * kstep;
;             const char* a2 = last ? nA : cA + (size_t)(t + 2) * kstep; const char* b2 = last ? nB : cB + (size_t)(t + 2) * kstep;
;             const char* a3 = a2 + kstep; const char* b3 = b2 + kstep;
;             PG8_LDB(B0, 0, 0); PG8_LDB(B1, 0, 1); PG8_SCHED; PG8_LDA(At, 0, 0); PG8_STAGE(PG8_SA(1, 1), a1 + hstepA, voffA);
.Lmy_gu_issue:
	s_cmp_lt_i32 s12, 64
	s_cbranch_scc1 .Lmy_gu_cont
	s_cmp_eq_u64 s[0:1], 0
	s_cbranch_scc1 .Lmy_gu_cont
	s_add_u32 s98, s27, 0xf4000148
	s_addc_u32 s99, s28, -1
	v_mov_b32_e32 v255, 0
	global_load_dword v255, v255, s[98:99] sc0 sc1
	s_branch .Lmy_gu_cont
.Lmy_gu_check:
	s_cmp_lt_i32 s12, 64
	s_cbranch_scc1 .Lmy_gu_cont
	s_cmp_eq_u64 s[0:1], 0
	s_cbranch_scc1 .Lmy_gu_cont
	s_lshl_b32 s74, s96, 10
	s_addk_i32 s74, 0x200
	v_readfirstlane_b32 s98, v255
	s_cmp_ge_u32 s98, s74
	s_cbranch_scc1 .Lmy_gu_cont
	s_mov_b32 s32, 0
.Lmy_gu_slow:
	s_waitcnt vmcnt(0)
	v_readfirstlane_b32 s98, v255
	s_cmp_ge_u32 s98, s74
	s_cbranch_scc1 .Lmy_gu_cont
	s_add_i32 s32, s32, 1
	s_cmp_lt_u32 s32, 0x800
	s_cbranch_scc0 .Lmy_gu_cont
	s_sleep 1
	s_add_u32 s98, s27, 0xf4000148
	s_addc_u32 s99, s28, -1
	v_mov_b32_e32 v255, 0
	global_load_dword v255, v255, s[98:99] sc0 sc1
	s_branch .Lmy_gu_slow

; #define PG8_STAGE(bufoff, gbase, voff) do { _Pragma("unroll") for (int _i = 0; _i < 2; ++_i) \
;         __builtin_amdgcn_global_load_lds((const unsigned*)((const char*)(gbase) + (voff)[_i]), (LAS unsigned*)(lds + (bufoff) + ldsw + _i * 8192), 16, 0, 0); } while (0)
; #define PG8_LDA(dst, b, h) do { _Pragma("unroll") for (int m = 0; m < 4; ++m) _Pragma("unroll") for (int k = 0; k < 2; ++k) dst[m][k] = *(const LAS bf16x8*)(lds + PG8_SA(b, h) + aoff + m * 2048 + k * 1024); } while (0)
; #define PG8_LDB(dst, b, h) do { _Pragma("unroll") for (int n = 0; n < 2; ++n) _Pragma("unroll") for (int k = 0; k < 2; ++k) dst[n][k] = *(const LAS bf16x8*)(lds + PG8_SB(b, h) + boff + n * 2048 + k * 1024); } while (0)
; #define PG8_SCHED __builtin_amdgcn_sched_barrier(0)
; template <class Epi, bool ALIGN_EPI>
; __device__ __forceinline__ void gemm_phase(LAS unsigned char* lds, const Gemm g, const Order& S, const Epi& E, const int wave_id) {
;     ...
;         for (int t = 0; t < nt; t += 2) {
;             const bool last = (t == nt - 2);
;             const char* a1 = cA + (size_t)(t + 1) * kstep;
;             const char* a2 = last ? nA : cA + (size_t)(t + 2) * kstep; const char* b2 = last ? nB : cB + (size_t)(t + 2) * kstep;
;             const char* a3 = a2 + kstep; const char* b3 = b2 + kstep;
;             PG8_LDB(B0, 0, 0); PG8_LDB(B1, 0, 1); PG8_SCHED; PG8_LDA(At, 0, 0); PG8_STAGE(PG8_SA(1, 1), a1 + hstepA, voffA);
.LBB0_1789:
	s_cmp_eq_u32 s50, 8
	s_cbranch_scc1 .Lmy_gu_issue
	s_cmp_eq_u32 s50, 12
	s_cbranch_scc1 .Lmy_gu_check

; #define INP(i) ((const float*)ld_ptr(pb, (i)))
; template <bool FINAL>
; __device__ __forceinline__ void norm_rows(const float* xp, const float* xs, const float* X, const float* g, const float* sh, const float* sc, bf16_t* XN, float* out, int gw, int NGW, int lane, const float* part, int nsplit) {
;     f32x4 vnext[4];
;     if (gw < M) { const float* xr0 = xp ? (gw < MP ? xp + (size_t)gw * D : xs + (size_t)(gw - MP) * D) : X + (size_t)gw * D;
; #pragma unroll
;         for (int j = 0; j < 4; ++j) vnext[j] = *(const f32x4*)(xr0 + 4 * lane + 256 * j); }
;     for (int row = gw; row < M; row += NGW) {
; __global__ void __launch_bounds__(512, 2) hybrid_fwd(Params P) {
;     ...
;         if (l + 1 < DEPTH) norm_rows<false>(nullptr, nullptr, X, INP(9) + (l + 1) * D, (MOD + (size_t)l * NMODROWS * 6144) + (size_t)NMODROWS * 6144, (MOD + (size_t)l * NMODROWS * 6144) + (size_t)NMODROWS * 6144 + 1024, XN, nullptr, gw, NGW, lane, (const float*)(ws + WS_PART), DFF / 256);
.LBB0_2087:
	v_readlane_b32 s1, v253, 7
	v_readlane_b32 s18, v253, 1
	v_readlane_b32 s0, v253, 0
	v_readlane_b32 s14, v253, 2
	v_mov_b32_e32 v207, s1
	v_mbcnt_lo_u32_b32 v160, -1, 0
	v_mbcnt_hi_u32_b32 v160, -1, v160
	ds_read2_b64 v[0:3], v207 offset0:34 offset1:35
	s_lshl_b32 s0, s0, 3
	s_lshl_b32 s4, s18, 3
	s_add_i32 s6, s0, s14
	s_add_i32 s6, s6, 0x3a00
	s_cmpk_lt_i32 s6, 0x4000
	s_cselect_b32 s6, 0x7fff, s6
	s_cmp_eq_u32 s96, 3
	s_waitcnt lgkmcnt(0)
	v_readfirstlane_b32 s3, v3
	v_readfirstlane_b32 s2, v2
	v_readfirstlane_b32 s15, v1
	v_readfirstlane_b32 s16, v0
	s_mov_b64 s[0:1], -1
	s_mov_b32 s17, 0x200000
	s_mov_b32 s19, 0x600000
	s_mov_b32 s22, 0x800000
	s_cbranch_scc1 .LBB0_2096
	ds_read_b64 v[0:1], v207 offset:72
	s_cmpk_gt_i32 s6, 0x41ff
	s_waitcnt lgkmcnt(0)
	v_readfirstlane_b32 s0, v1
	v_readfirstlane_b32 s1, v0
	s_cbranch_scc1 .LBB0_2095
	s_mul_i32 s74, s96, 0xc6000
	s_lshl_b64 s[8:9], s[74:75], 2
	s_add_u32 s8, s2, s8
	s_addc_u32 s9, s3, s9
	s_add_u32 s10, s2, 0x7e00000
	s_addc_u32 s11, s3, 0
	s_lshl_b32 s74, s96, 10
	s_lshl_b64 s[12:13], s[74:75], 2
	s_add_u32 s12, s1, s12
	s_addc_u32 s13, s0, s13
	s_ashr_i32 s7, s6, 31
	s_lshl_b64 s[0:1], s[6:7], 12
	v_lshlrev_b32_e32 v0, 2, v160
	s_add_u32 s0, s10, s0
	v_ashrrev_i32_e32 v1, 31, v0
	s_addc_u32 s1, s11, s1
	v_lshlrev_b64 v[2:3], 2, v[0:1]
	v_lshl_add_u64 v[4:5], s[0:1], 0, v[2:3]
	global_load_dwordx4 v[24:27], v[4:5], off
	global_load_dwordx4 v[20:23], v[4:5], off offset:1024
	global_load_dwordx4 v[16:19], v[4:5], off offset:2048
	global_load_dwordx4 v[28:31], v[4:5], off offset:3072
	v_lshl_add_u64 v[4:5], s[2:3], 0, v[2:3]
	s_mov_b64 s[0:1], 0x13c00000
	v_lshl_add_u64 v[184:185], v[4:5], 0, s[0:1]
	v_lshl_add_u64 v[4:5], s[12:13], 0, v[2:3]
	s_mov_b64 s[0:1], 0x1000
	v_lshl_add_u64 v[186:187], s[10:11], 0, v[2:3]
	v_lshl_add_u64 v[188:189], v[4:5], 0, s[0:1]
	v_lshl_add_u64 v[2:3], s[8:9], 0, v[2:3]
	s_mov_b64 s[0:1], 0xb19000
	v_lshl_add_u64 v[190:191], v[2:3], 0, s[0:1]
	s_mov_b64 s[0:1], 0xb18000
	v_lshl_add_u64 v[192:193], v[2:3], 0, s[0:1]
	s_lshl_b64 s[0:1], s[6:7], 11
	s_add_u32 s0, s2, s0
	s_addc_u32 s1, s3, s1
	v_lshl_add_u64 v[0:1], v[0:1], 1, s[0:1]
	s_mov_b64 s[0:1], 0xc000000
	s_ashr_i32 s5, s4, 31
	v_lshl_add_u64 v[194:195], v[0:1], 0, s[0:1]
	s_lshl_b64 s[8:9], s[4:5], 11
	s_mov_b32 s0, s6
	s_branch .LBB0_2091
; __device__ __forceinline__ unsigned cvt_pk_bf16(float lo, float hi) { const f32x2_t v = {lo, hi}; const bf16x2_t b = __builtin_convertvector(v, bf16x2_t); return __builtin_bit_cast(unsigned, b); }
; template <bool FINAL>
; __device__ __forceinline__ void norm_rows(const float* xp, const float* xs, const float* X, const float* g, const float* sh, const float* sc, bf16_t* XN, float* out, int gw, int NGW, int lane, const float* part, int nsplit) {
;     ...
;         for (int j = 0; j < 4; ++j) s += (v[j][0] * v[j][0] + v[j][1] * v[j][1]) + (v[j][2] * v[j][2] + v[j][3] * v[j][3]);
;         const float rstd = 1.0f / sqrtf(wave_sum(s) * (1.0f / D) + EPS);
;         const int mr = mod_row(row);
;         if (!FINAL && xp && row >= MP) {
; #pragma unroll
;             for (int j = 0; j < 4; ++j) *(f32x4*)((float*)X + (size_t)row * D + 4 * lane + 256 * j) = v[j]; }
; #pragma unroll
;         for (int j = 0; j < 4; ++j) { const int col = 4 * lane + 256 * j; const f32x4 gg = *(const f32x4*)(g + col);
;             if (FINAL) { *(f32x4*)(out + (size_t)row * D + col) = v[j] * rstd * gg; }
;             else { const f32x4 s1 = *(const f32x4*)(sc + (size_t)mr * 6144 + col), s0 = *(const f32x4*)(sh + (size_t)mr * 6144 + col);
;                 const f32x4 h = v[j] * rstd * gg * (s1 + 1.0f) + s0;
;                 *(u32x2*)(XN + (size_t)row * D + col) = (u32x2){cvt_pk_bf16(h[0], h[1]), cvt_pk_bf16(h[2], h[3])}; } }
.LBB0_2090:
	v_mul_f32_e32 v32, v25, v25
	v_mul_f32_e32 v33, v27, v27
	v_fmac_f32_e32 v32, v24, v24
	v_fmac_f32_e32 v33, v26, v26
	v_add_f32_e32 v32, v32, v33
	v_mul_f32_e32 v33, v21, v21
	v_mul_f32_e32 v34, v23, v23
	v_fmac_f32_e32 v33, v20, v20
	v_fmac_f32_e32 v34, v22, v22
	v_add_f32_e32 v33, v33, v34
	v_add_f32_e32 v32, v32, v33
	v_mul_f32_e32 v33, v17, v17
	v_mul_f32_e32 v34, v19, v19
	v_fmac_f32_e32 v33, v16, v16
	v_fmac_f32_e32 v34, v18, v18
	v_add_f32_e32 v33, v33, v34
	v_add_f32_e32 v32, v33, v32
	v_mul_f32_e32 v33, v29, v29
	v_mul_f32_e32 v34, v31, v31
	v_fmac_f32_e32 v33, v28, v28
	v_fmac_f32_e32 v34, v30, v30
	v_add_f32_e32 v33, v33, v34
	v_add_f32_e32 v32, v33, v32
	ds_swizzle_b32 v33, v32 offset:swizzle(SWAP,1)
	s_lshr_b32 s5, s74, 2
	s_ashr_i32 s1, s0, 12
	s_add_i32 s5, s5, 4
	s_cmpk_lt_i32 s0, 0x4000
	s_waitcnt lgkmcnt(0)
	v_add_f32_e32 v32, v32, v33
	ds_swizzle_b32 v33, v32 offset:swizzle(SWAP,2)
	s_cselect_b32 s5, s1, s5
	v_mad_i64_i32 v[44:45], s[0:1], s5, v206, v[190:191]
	v_mad_i64_i32 v[46:47], s[0:1], s5, v206, v[192:193]
	s_waitcnt lgkmcnt(0)
	v_add_f32_e32 v32, v32, v33
	ds_swizzle_b32 v33, v32 offset:swizzle(SWAP,4)
	s_waitcnt lgkmcnt(0)
	v_add_f32_e32 v32, v32, v33
	ds_swizzle_b32 v33, v32 offset:swizzle(SWAP,8)
	s_waitcnt lgkmcnt(0)
	v_add_f32_e32 v32, v32, v33
	ds_swizzle_b32 v33, v32 offset:swizzle(SWAP,16)
	s_waitcnt lgkmcnt(0)
	v_add_f32_e32 v48, v32, v33
	v_mov_b32_e32 v49, v48
	s_nop 1
	v_permlane32_swap_b32 v49, v48
	s_nop 1
	global_load_dwordx4 v[32:35], v[188:189], off
	global_load_dwordx4 v[36:39], v[44:45], off
	global_load_dwordx4 v[40:43], v[46:47], off
	v_add_f32_e32 v48, v49, v48
	v_fmamk_f32 v48, v48, 0x3a800000, v202
	v_mul_f32_e32 v49, 0x4f800000, v48
	v_cmp_gt_f32_e32 vcc, s95, v48
	s_nop 1
	v_cndmask_b32_e32 v48, v48, v49, vcc
	v_sqrt_f32_e32 v49, v48
	s_nop 0
	v_add_u32_e32 v50, -1, v49
	v_add_u32_e32 v51, 1, v49
	v_fma_f32 v52, -v50, v49, v48
	v_fma_f32 v53, -v51, v49, v48
	v_cmp_ge_f32_e64 s[0:1], 0, v52
	s_nop 1
	v_cndmask_b32_e64 v49, v49, v50, s[0:1]
	v_cmp_lt_f32_e64 s[0:1], 0, v53
	s_nop 1
	v_cndmask_b32_e64 v49, v49, v51, s[0:1]
	v_mul_f32_e32 v50, 0x37800000, v49
	v_cndmask_b32_e32 v49, v49, v50, vcc
	v_cmp_class_f32_e32 vcc, v48, v203
	s_nop 1
	v_cndmask_b32_e32 v48, v49, v48, vcc
	v_div_scale_f32 v49, s[0:1], v48, v48, 1.0
	v_rcp_f32_e32 v50, v49
	v_div_scale_f32 v51, vcc, 1.0, v48, 1.0
	s_mov_b32 s0, s10
	v_fma_f32 v52, -v49, v50, 1.0
	v_fmac_f32_e32 v50, v52, v50
	v_mul_f32_e32 v52, v51, v50
	v_fma_f32 v53, -v49, v52, v51
	v_fmac_f32_e32 v52, v53, v50
	v_fma_f32 v49, -v49, v52, v51
	v_div_fmas_f32 v49, v49, v50, v52
	v_div_fixup_f32 v48, v49, v48, 1.0
	v_pk_mul_f32 v[26:27], v[26:27], v[48:49] op_sel_hi:[1,0]
	v_pk_mul_f32 v[24:25], v[24:25], v[48:49] op_sel_hi:[1,0]
	v_pk_mul_f32 v[22:23], v[22:23], v[48:49] op_sel_hi:[1,0]
	v_pk_mul_f32 v[20:21], v[20:21], v[48:49] op_sel_hi:[1,0]
	v_pk_mul_f32 v[18:19], v[18:19], v[48:49] op_sel_hi:[1,0]
	v_pk_mul_f32 v[16:17], v[16:17], v[48:49] op_sel_hi:[1,0]
	s_and_b64 vcc, exec, s[12:13]
	s_waitcnt vmcnt(2)
	v_pk_mul_f32 v[24:25], v[32:33], v[24:25]
	v_pk_mul_f32 v[26:27], v[34:35], v[26:27]
	s_waitcnt vmcnt(1)
	v_pk_add_f32 v[32:33], v[38:39], 1.0 op_sel_hi:[1,0]
	v_pk_add_f32 v[34:35], v[36:37], 1.0 op_sel_hi:[1,0]
	s_waitcnt vmcnt(0)
	v_pk_fma_f32 v[26:27], v[32:33], v[26:27], v[42:43]
	v_pk_fma_f32 v[24:25], v[34:35], v[24:25], v[40:41]
	s_nop 0
	v_cvt_pk_bf16_f32 v24, v24, v25
	v_cvt_pk_bf16_f32 v25, v26, v27
	global_store_dwordx2 v[194:195], v[24:25], off sc0 sc1
	global_load_dwordx4 v[24:27], v[188:189], off offset:1024
	s_nop 0
	global_load_dwordx4 v[32:35], v[44:45], off offset:1024
	global_load_dwordx4 v[36:39], v[46:47], off offset:1024
	s_waitcnt vmcnt(2)
	v_pk_mul_f32 v[20:21], v[24:25], v[20:21]
	v_pk_mul_f32 v[22:23], v[26:27], v[22:23]
	s_waitcnt vmcnt(1)
	v_pk_add_f32 v[24:25], v[34:35], 1.0 op_sel_hi:[1,0]
	v_pk_add_f32 v[26:27], v[32:33], 1.0 op_sel_hi:[1,0]
	s_waitcnt vmcnt(0)
	v_pk_fma_f32 v[22:23], v[24:25], v[22:23], v[38:39]
	v_pk_fma_f32 v[20:21], v[26:27], v[20:21], v[36:37]
	s_nop 0
	v_cvt_pk_bf16_f32 v20, v20, v21
	v_cvt_pk_bf16_f32 v21, v22, v23
	global_store_dwordx2 v[194:195], v[20:21], off offset:512 sc0 sc1
	global_load_dwordx4 v[20:23], v[188:189], off offset:2048
	s_nop 0
	global_load_dwordx4 v[24:27], v[44:45], off offset:2048
	global_load_dwordx4 v[32:35], v[46:47], off offset:2048
	s_waitcnt vmcnt(2)
	v_pk_mul_f32 v[16:17], v[16:17], v[20:21]
	v_pk_mul_f32 v[18:19], v[18:19], v[22:23]
	s_waitcnt vmcnt(1)
	v_pk_add_f32 v[20:21], v[26:27], 1.0 op_sel_hi:[1,0]
	v_pk_add_f32 v[22:23], v[24:25], 1.0 op_sel_hi:[1,0]
	s_waitcnt vmcnt(0)
	v_pk_fma_f32 v[18:19], v[18:19], v[20:21], v[34:35]
	v_pk_fma_f32 v[16:17], v[16:17], v[22:23], v[32:33]
	v_mov_b32_e32 v24, v0
	v_cvt_pk_bf16_f32 v16, v16, v17
	v_cvt_pk_bf16_f32 v17, v18, v19
	global_store_dwordx2 v[194:195], v[16:17], off offset:1024 sc0 sc1
	global_load_dwordx4 v[32:35], v[188:189], off offset:3072
	global_load_dwordx4 v[36:39], v[44:45], off offset:3072
	global_load_dwordx4 v[40:43], v[46:47], off offset:3072
	v_pk_mul_f32 v[44:45], v[30:31], v[48:49] op_sel_hi:[1,0]
	v_pk_mul_f32 v[46:47], v[28:29], v[48:49] op_sel_hi:[1,0]
	v_mov_b32_e32 v25, v1
	v_mov_b32_e32 v26, v2
	v_mov_b32_e32 v27, v3
	v_mov_b32_e32 v20, v4
	v_mov_b32_e32 v21, v5
	v_mov_b32_e32 v22, v6
	v_mov_b32_e32 v23, v7
	v_mov_b32_e32 v16, v8
	v_mov_b32_e32 v17, v9
	v_mov_b32_e32 v18, v10
	v_mov_b32_e32 v19, v11
	v_mov_b32_e32 v28, v12
	v_mov_b32_e32 v29, v13
	v_mov_b32_e32 v30, v14
	v_mov_b32_e32 v31, v15
	s_waitcnt vmcnt(2)
	v_pk_mul_f32 v[0:1], v[46:47], v[32:33]
	v_pk_mul_f32 v[2:3], v[44:45], v[34:35]
	s_waitcnt vmcnt(1)
	v_pk_add_f32 v[4:5], v[38:39], 1.0 op_sel_hi:[1,0]
	v_pk_add_f32 v[6:7], v[36:37], 1.0 op_sel_hi:[1,0]
	s_waitcnt vmcnt(0)
	v_pk_fma_f32 v[2:3], v[2:3], v[4:5], v[42:43]
	v_pk_fma_f32 v[0:1], v[0:1], v[6:7], v[40:41]
	s_nop 0
	v_cvt_pk_bf16_f32 v0, v0, v1
	v_cvt_pk_bf16_f32 v1, v2, v3
	global_store_dwordx2 v[194:195], v[0:1], off offset:1536 sc0 sc1
	v_lshl_add_u64 v[194:195], v[194:195], 0, s[8:9]
	s_cbranch_vccnz .Lmy_nf1_arr

; #define INP(i) ((const float*)ld_ptr(pb, (i)))
; #define PHASE_END if (ph + 1 < hi) grid_barrier((unsigned*)ws, (unsigned)G, tid, (volatile LAS unsigned*)(ldsl + XBST_OFF)); } ++ph;
; __global__ void __launch_bounds__(512, 2) hybrid_fwd(Params P) {
;     ...
;         PHASE_BEGIN
;         if (l + 1 < DEPTH) norm_rows<false>(nullptr, nullptr, X, INP(9) + (l + 1) * D, (MOD + (size_t)l * NMODROWS * 6144) + (size_t)NMODROWS * 6144, (MOD + (size_t)l * NMODROWS * 6144) + (size_t)NMODROWS * 6144 + 1024, XN, nullptr, gw, NGW, lane, (const float*)(ws + WS_PART), DFF / 256);
;         else norm_rows<true>(nullptr, nullptr, X, INP(33), nullptr, nullptr, nullptr, out, gw, NGW, lane, (const float*)(ws + WS_PART), DFF / 256);
;         PHASE_END
.LBB0_2104:
	s_add_i32 s22, s73, 9
	s_getpc_b64 s[98:99]

; __global__ void __launch_bounds__(512, 2) hybrid_fwd(Params P) {
	.amdhsa_kernel _Z10hybrid_fwd6Params
		.amdhsa_group_segment_fixed_size 0
		.amdhsa_private_segment_fixed_size 0
		.amdhsa_kernarg_size 552
		.amdhsa_user_sgpr_count 2
		.amdhsa_user_sgpr_dispatch_ptr 0
		.amdhsa_user_sgpr_queue_ptr 0
		.amdhsa_user_sgpr_kernarg_segment_ptr 1
		.amdhsa_user_sgpr_dispatch_id 0
		.amdhsa_user_sgpr_kernarg_preload_length 0
		.amdhsa_user_sgpr_kernarg_preload_offset 0
		.amdhsa_user_sgpr_private_segment_size 0
		.amdhsa_uses_dynamic_stack 0
		.amdhsa_enable_private_segment 0
		.amdhsa_system_sgpr_workgroup_id_x 1
		.amdhsa_system_sgpr_workgroup_id_y 0
		.amdhsa_system_sgpr_workgroup_id_z 0
		.amdhsa_system_sgpr_workgroup_info 0
		.amdhsa_system_vgpr_workitem_id 2
		.amdhsa_next_free_vgpr 256
		.amdhsa_next_free_sgpr 100
		.amdhsa_accum_offset 256
		.amdhsa_reserve_vcc 1
		.amdhsa_float_round_mode_32 0
		.amdhsa_float_round_mode_16_64 0
		.amdhsa_float_denorm_mode_32 3
		.amdhsa_float_denorm_mode_16_64 3
		.amdhsa_dx10_clamp 1
		.amdhsa_ieee_mode 1
		.amdhsa_fp16_overflow 0
		.amdhsa_tg_split 0
		.amdhsa_exception_fp_ieee_invalid_op 0
		.amdhsa_exception_fp_denorm_src 0
		.amdhsa_exception_fp_ieee_div_zero 0
		.amdhsa_exception_fp_ieee_overflow 0
		.amdhsa_exception_fp_ieee_underflow 0
		.amdhsa_exception_fp_ieee_inexact 0
		.amdhsa_exception_int_div_zero 0
	.end_amdhsa_kernel

; __global__ void __launch_bounds__(512, 2) hybrid_fwd(Params P) {
amdhsa.kernels:
  - .agpr_count:     0
    .args:
      - .offset:         0
        .size:           296
        .value_kind:     by_value
      - .offset:         296
        .size:           4
        .value_kind:     hidden_block_count_x
      - .offset:         300
        .size:           4
        .value_kind:     hidden_block_count_y
      - .offset:         304
        .size:           4
        .value_kind:     hidden_block_count_z
      - .offset:         308
        .size:           2
        .value_kind:     hidden_group_size_x
      - .offset:         310
        .size:           2
        .value_kind:     hidden_group_size_y
      - .offset:         312
        .size:           2
        .value_kind:     hidden_group_size_z
      - .offset:         314
        .size:           2
        .value_kind:     hidden_remainder_x
      - .offset:         316
        .size:           2
        .value_kind:     hidden_remainder_y
      - .offset:         318
        .size:           2
        .value_kind:     hidden_remainder_z
      - .offset:         336
        .size:           8
        .value_kind:     hidden_global_offset_x
      - .offset:         344
        .size:           8
        .value_kind:     hidden_global_offset_y
      - .offset:         352
        .size:           8
        .value_kind:     hidden_global_offset_z
      - .offset:         360
        .size:           2
        .value_kind:     hidden_grid_dims
      - .offset:         384
        .size:           8
        .value_kind:     hidden_multigrid_sync_arg
      - .offset:         416
        .size:           4
        .value_kind:     hidden_dynamic_lds_size
    .group_segment_fixed_size: 0
    .kernarg_segment_align: 8
    .kernarg_segment_size: 552
    .language:       OpenCL C
    .language_version:
      - 2
      - 0
    .max_flat_workgroup_size: 512
    .name:           _Z10hybrid_fwd6Params
    .private_segment_fixed_size: 0
    .sgpr_count:     106
    .sgpr_spill_count: 272
    .symbol:         _Z10hybrid_fwd6Params.kd
    .uniform_work_group_size: 1
    .uses_dynamic_stack: false
    .vgpr_count:     256
    .vgpr_spill_count: 0
    .wavefront_size: 64
